# every workgroup also issues the L2 write-back on barrier arrival (not only the XCD leader), on top of v36
# baseline (speedup 1.0000x reference)
.LBB0_66:
	s_or_b64 exec, exec, s[6:7]
	v_cvt_f32_u32_e32 v5, v3
	s_waitcnt vmcnt(0)
	v_readfirstlane_b32 s4, v4
	v_sub_u32_e32 v4, 0, v3
	v_rcp_iflag_f32_e32 v5, v5
	v_add_u32_e32 v6, s4, v2
	v_mul_f32_e32 v5, 0x4f7ffffe, v5
	v_cvt_u32_f32_e32 v5, v5
	v_mul_lo_u32 v2, v4, v5
	v_mul_hi_u32 v2, v5, v2
	v_add_u32_e32 v2, v5, v2
	v_mul_hi_u32 v2, v6, v2
	v_mul_lo_u32 v4, v2, v3
	v_sub_u32_e32 v4, v6, v4
	v_add_u32_e32 v5, 1, v2
	v_cmp_ge_u32_e32 vcc, v4, v3
	s_nop 1
	v_cndmask_b32_e32 v2, v2, v5, vcc
	v_sub_u32_e32 v5, v4, v3
	v_cndmask_b32_e32 v4, v4, v5, vcc
	v_add_u32_e32 v5, 1, v2
	v_cmp_ge_u32_e32 vcc, v4, v3
	v_add_u32_e32 v4, 1, v6
	s_nop 0
	v_cndmask_b32_e32 v2, v2, v5, vcc
	v_mul_lo_u32 v5, v3, v2
	v_add_u32_e32 v3, v5, v3
	v_cmp_ne_u32_e32 vcc, v4, v3
	s_and_saveexec_b64 s[4:5], vcc
	s_xor_b64 s[4:5], exec, s[4:5]
	s_cbranch_execz .LBB0_80
	buffer_wbl2 sc1
	buffer_inv sc1
	s_waitcnt lgkmcnt(0)
	v_mov_b32_e32 v1, 0x2000
	global_load_dword v1, v1, s[2:3] offset:1024 sc1
	s_add_u32 s10, s2, 0x2400
	s_addc_u32 s11, s3, 0
	s_waitcnt vmcnt(0)
	v_cmp_eq_u32_e32 vcc, v1, v2
	s_and_saveexec_b64 s[6:7], vcc
	s_cbranch_execz .LBB0_79
	s_add_u32 s8, s74, 0x4200
	s_addc_u32 s9, s75, 0
	s_mov_b32 s13, 1
	s_mov_b64 s[16:17], 0
	v_mov_b32_e32 v1, 0
	s_branch .LBB0_70

.LBB0_179:
	s_or_b64 exec, exec, s[6:7]
	v_cvt_f32_u32_e32 v5, v3
	s_waitcnt vmcnt(0)
	v_readfirstlane_b32 s4, v4
	v_sub_u32_e32 v4, 0, v3
	v_rcp_iflag_f32_e32 v5, v5
	v_add_u32_e32 v6, s4, v2
	v_mul_f32_e32 v5, 0x4f7ffffe, v5
	v_cvt_u32_f32_e32 v5, v5
	v_mul_lo_u32 v2, v4, v5
	v_mul_hi_u32 v2, v5, v2
	v_add_u32_e32 v2, v5, v2
	v_mul_hi_u32 v2, v6, v2
	v_mul_lo_u32 v4, v2, v3
	v_sub_u32_e32 v4, v6, v4
	v_add_u32_e32 v5, 1, v2
	v_cmp_ge_u32_e32 vcc, v4, v3
	s_nop 1
	v_cndmask_b32_e32 v2, v2, v5, vcc
	v_sub_u32_e32 v5, v4, v3
	v_cndmask_b32_e32 v4, v4, v5, vcc
	v_add_u32_e32 v5, 1, v2
	v_cmp_ge_u32_e32 vcc, v4, v3
	v_add_u32_e32 v4, 1, v6
	s_nop 0
	v_cndmask_b32_e32 v2, v2, v5, vcc
	v_mul_lo_u32 v5, v3, v2
	v_add_u32_e32 v3, v5, v3
	v_cmp_ne_u32_e32 vcc, v4, v3
	s_and_saveexec_b64 s[4:5], vcc
	s_xor_b64 s[4:5], exec, s[4:5]
	s_cbranch_execz .LBB0_193
	buffer_wbl2 sc1
	buffer_inv sc1
	s_waitcnt lgkmcnt(0)
	v_mov_b32_e32 v1, 0x2000
	global_load_dword v1, v1, s[2:3] offset:1024 sc1
	s_add_u32 s10, s2, 0x2400
	s_addc_u32 s11, s3, 0
	s_waitcnt vmcnt(0)
	v_cmp_eq_u32_e32 vcc, v1, v2
	s_and_saveexec_b64 s[6:7], vcc
	s_cbranch_execz .LBB0_192
	s_add_u32 s8, s74, 0x4200
	s_addc_u32 s9, s75, 0
	s_mov_b32 s12, 1
	s_mov_b64 s[16:17], 0
	v_mov_b32_e32 v1, 0
	s_branch .LBB0_183

.LBB0_997:
	s_or_b64 exec, exec, s[6:7]
	v_cvt_f32_u32_e32 v5, v3
	s_waitcnt vmcnt(0)
	v_readfirstlane_b32 s4, v4
	v_sub_u32_e32 v4, 0, v3
	v_rcp_iflag_f32_e32 v5, v5
	v_add_u32_e32 v6, s4, v2
	v_mul_f32_e32 v5, 0x4f7ffffe, v5
	v_cvt_u32_f32_e32 v5, v5
	v_mul_lo_u32 v2, v4, v5
	v_mul_hi_u32 v2, v5, v2
	v_add_u32_e32 v2, v5, v2
	v_mul_hi_u32 v2, v6, v2
	v_mul_lo_u32 v4, v2, v3
	v_sub_u32_e32 v4, v6, v4
	v_add_u32_e32 v5, 1, v2
	v_cmp_ge_u32_e32 vcc, v4, v3
	s_nop 1
	v_cndmask_b32_e32 v2, v2, v5, vcc
	v_sub_u32_e32 v5, v4, v3
	v_cndmask_b32_e32 v4, v4, v5, vcc
	v_add_u32_e32 v5, 1, v2
	v_cmp_ge_u32_e32 vcc, v4, v3
	v_add_u32_e32 v4, 1, v6
	s_nop 0
	v_cndmask_b32_e32 v2, v2, v5, vcc
	v_mul_lo_u32 v5, v3, v2
	v_add_u32_e32 v3, v5, v3
	v_cmp_ne_u32_e32 vcc, v4, v3
	s_and_saveexec_b64 s[4:5], vcc
	s_xor_b64 s[4:5], exec, s[4:5]
	s_cbranch_execz .LBB0_1011
	buffer_wbl2 sc1
	buffer_inv sc1
	s_waitcnt lgkmcnt(0)
	v_mov_b32_e32 v1, 0x2000
	global_load_dword v1, v1, s[2:3] offset:1024 sc1
	s_add_u32 s10, s2, 0x2400
	s_addc_u32 s11, s3, 0
	s_waitcnt vmcnt(0)
	v_cmp_eq_u32_e32 vcc, v1, v2
	s_and_saveexec_b64 s[6:7], vcc
	s_cbranch_execz .LBB0_1010
	s_add_u32 s8, s74, 0x4200
	s_addc_u32 s9, s75, 0
	s_mov_b32 s15, 1
	s_mov_b64 s[12:13], 0
	v_mov_b32_e32 v1, 0
	s_branch .LBB0_1001
